# prep1: dropped the redundant vmcnt(0) that made the phase wait for the record-zeroing store before issuing its first loads
# baseline (speedup 1.0000x reference)
.LBB0_396:
	s_andn2_b64 vcc, exec, s[0:1]
	s_cbranch_vccnz .LBB0_405
	v_readlane_b32 s6, v253, 0
	s_lshl_b32 s6, s6, 9
	v_add_u32_e32 v2, s6, v137
	v_mov_b32_e32 v4, 0
	v_mov_b32_e32 v5, 0
	v_mov_b32_e32 v6, 0
	v_mov_b32_e32 v7, 0
	s_add_u32 s8, s94, 0xc9d8000
	s_addc_u32 s9, s95, 0
	v_cmp_gt_u32_e32 vcc, 0x20000, v2
	v_lshlrev_b32_e32 v2, 4, v2
	s_and_saveexec_b64 s[22:23], vcc
	global_store_dwordx4 v2, v[4:7], s[8:9]
	s_or_b64 exec, exec, s[22:23]
	s_mov_b64 s[0:1], 0
	s_mov_b64 s[8:9], 0
	v_mov_b32_e32 v0, v137
	v_readlane_b32 s6, v254, 45
	v_ashrrev_i32_e32 v2, 6, v0
	s_nop 0
	v_add_u32_e32 v2, s6, v2
	s_movk_i32 s6, 0x1800
	v_cmp_gt_i32_e32 vcc, s6, v2
	s_and_saveexec_b64 s[22:23], vcc
	s_cbranch_execz .LBB0_404
	s_load_dword s6, s[78:79], 0x0
	v_lshlrev_b32_e32 v0, 2, v0
	s_add_u32 s0, s94, s0
	v_and_b32_e32 v8, 0xfc, v0
	s_addc_u32 s1, s95, s1
	v_lshlrev_b32_e32 v0, 2, v8
	s_add_u32 s26, s0, 0x6300000
	v_lshl_add_u64 v[4:5], s[0:1], 0, v[0:1]
	v_lshlrev_b32_e32 v0, 1, v8
	s_addc_u32 s27, s1, 0
	v_or_b32_e32 v10, 0x100, v8
	v_or_b32_e32 v12, 0x200, v8
	v_or_b32_e32 v14, 0x300, v8
	s_mov_b64 s[8:9], 0x6348000
	v_lshl_add_u64 v[6:7], s[0:1], 0, v[0:1]
	s_mov_b64 s[0:1], 0x7b48000
	s_waitcnt lgkmcnt(0)
	s_lshl_b32 s6, s6, 3
	v_lshl_add_u64 v[4:5], v[4:5], 0, s[8:9]
	v_lshl_add_u64 v[6:7], v[6:7], 0, s[0:1]
	s_mov_b64 s[34:35], 0
	v_lshlrev_b32_e32 v0, 2, v8
	v_lshlrev_b32_e32 v8, 2, v10
	v_lshlrev_b32_e32 v10, 2, v12
	v_lshlrev_b32_e32 v12, 2, v14
	s_branch .LBB0_400
